# SSD conv4+silu blocks rewritten with channel-pair packed f32 FMA (x,B,C), ds_read hoisting, counted vmcnt
# speedup vs baseline: 1.0119x; 1.0119x over previous
; __device__ __forceinline__ float silu_f(float v) { return v * __builtin_amdgcn_rcpf(1.f + __expf(-v)); }
; __device__ __forceinline__ void conv_rows(const u32x4 (&rawp)[5], const float* wl, float (&o0)[8], float (&o1)[8]) {
;     float raw[5][8];
; #pragma unroll
;     for (int q = 0; q < 5; ++q) unpack8(rawp[q], raw[q]);
; #pragma unroll
;     for (int h = 0; h < 2; ++h) {
;         const f32x4 bv = *(const f32x4*)(wl + 4 * 128 + h * 4);
;         f32x4 a0 = bv, a1 = bv;
; #pragma unroll
;         for (int k = 0; k < 4; ++k) { const f32x4 wv = *(const f32x4*)(wl + k * 128 + h * 4);
; #pragma unroll
;             for (int i = 0; i < 4; ++i) { a0[i] += wv[i] * raw[k][h * 4 + i]; a1[i] += wv[i] * raw[k + 1][h * 4 + i]; } }
; #pragma unroll
;         for (int i = 0; i < 4; ++i) { o0[h * 4 + i] = silu_f(a0[i]); o1[h * 4 + i] = silu_f(a1[i]); }
;         __builtin_amdgcn_sched_barrier(0);
;     }
; }
; __device__ __forceinline__ void phase_ssd(const Params& p, uchar* sm, int j, bf16_t* zx, const float* dtraw, float* ssqb) {
;     ...
;             conv_rows(rx, wlx, xo0, xo1);
.LBB0_466:
	ds_read_b128 v[132:135], v187 offset:2048
	ds_read_b128 v[96:99], v187 offset:0
	ds_read_b128 v[120:123], v187 offset:512
	ds_read_b128 v[124:127], v187 offset:1024
	v_mov_b32_e32 v100, 0xbfb8aa3b
	v_mov_b32_e32 v101, 0xbfb8aa3b
	v_mov_b32_e32 v118, 1.0
	v_mov_b32_e32 v119, 1.0
	ds_read_b128 v[128:131], v187 offset:1536
	s_nop 0
	v_lshlrev_b32_e32 v144, 16, v4
	v_and_b32_e32 v145, 0xffff0000, v4
	v_lshlrev_b32_e32 v178, 16, v5
	v_and_b32_e32 v179, 0xffff0000, v5
	s_waitcnt lgkmcnt(3)
	v_pk_fma_f32 v[180:181], v[96:97], v[144:145], v[132:133]
	v_pk_fma_f32 v[230:231], v[98:99], v[178:179], v[134:135]
	v_lshlrev_b32_e32 v144, 16, v8
	v_and_b32_e32 v145, 0xffff0000, v8
	v_lshlrev_b32_e32 v178, 16, v9
	v_and_b32_e32 v179, 0xffff0000, v9
	s_waitcnt lgkmcnt(2)
	v_pk_fma_f32 v[180:181], v[120:121], v[144:145], v[180:181]
	v_pk_fma_f32 v[230:231], v[122:123], v[178:179], v[230:231]
	v_pk_fma_f32 v[232:233], v[96:97], v[144:145], v[132:133]
	v_pk_fma_f32 v[234:235], v[98:99], v[178:179], v[134:135]
	v_lshlrev_b32_e32 v144, 16, v12
	v_and_b32_e32 v145, 0xffff0000, v12
	v_lshlrev_b32_e32 v178, 16, v13
	v_and_b32_e32 v179, 0xffff0000, v13
	s_waitcnt lgkmcnt(1)
	v_pk_fma_f32 v[180:181], v[124:125], v[144:145], v[180:181]
	v_pk_fma_f32 v[230:231], v[126:127], v[178:179], v[230:231]
	v_pk_fma_f32 v[232:233], v[120:121], v[144:145], v[232:233]
	v_pk_fma_f32 v[234:235], v[122:123], v[178:179], v[234:235]
	v_lshlrev_b32_e32 v144, 16, v16
	v_and_b32_e32 v145, 0xffff0000, v16
	v_lshlrev_b32_e32 v178, 16, v17
	v_and_b32_e32 v179, 0xffff0000, v17
	s_waitcnt lgkmcnt(0)
	v_pk_fma_f32 v[180:181], v[128:129], v[144:145], v[180:181]
	v_pk_fma_f32 v[230:231], v[130:131], v[178:179], v[230:231]
	v_pk_fma_f32 v[232:233], v[124:125], v[144:145], v[232:233]
	v_pk_fma_f32 v[234:235], v[126:127], v[178:179], v[234:235]
	v_lshlrev_b32_e32 v144, 16, v24
	v_and_b32_e32 v145, 0xffff0000, v24
	v_lshlrev_b32_e32 v178, 16, v25
	v_and_b32_e32 v179, 0xffff0000, v25
	v_pk_fma_f32 v[232:233], v[128:129], v[144:145], v[232:233]
	v_pk_fma_f32 v[234:235], v[130:131], v[178:179], v[234:235]
	v_pk_mul_f32 v[96:97], v[180:181], v[100:101]
	v_pk_mul_f32 v[98:99], v[230:231], v[100:101]
	v_pk_mul_f32 v[120:121], v[232:233], v[100:101]
	v_pk_mul_f32 v[122:123], v[234:235], v[100:101]
	v_exp_f32_e32 v96, v96
	v_exp_f32_e32 v97, v97
	v_exp_f32_e32 v98, v98
	v_exp_f32_e32 v99, v99
	v_exp_f32_e32 v120, v120
	v_exp_f32_e32 v121, v121
	v_exp_f32_e32 v122, v122
	v_exp_f32_e32 v123, v123
	v_pk_add_f32 v[96:97], v[96:97], v[118:119]
	v_pk_add_f32 v[98:99], v[98:99], v[118:119]
	v_pk_add_f32 v[120:121], v[120:121], v[118:119]
	v_pk_add_f32 v[122:123], v[122:123], v[118:119]
	ds_read_b128 v[132:135], v187 offset:2064
	ds_read_b128 v[112:115], v187 offset:16
	v_rcp_f32_e32 v96, v96
	v_rcp_f32_e32 v97, v97
	v_rcp_f32_e32 v98, v98
	ds_read_b128 v[236:239], v187 offset:528
	v_rcp_f32_e32 v99, v99
	v_rcp_f32_e32 v120, v120
	v_rcp_f32_e32 v121, v121
	v_rcp_f32_e32 v122, v122
	ds_read_b128 v[124:127], v187 offset:1040
	v_rcp_f32_e32 v123, v123
	v_mul_f32_e32 v102, v180, v96
	v_mul_f32_e32 v104, v181, v97
	v_mul_f32_e32 v106, v230, v98
	v_mul_f32_e32 v108, v231, v99
	v_mul_f32_e32 v103, v232, v120
	v_mul_f32_e32 v105, v233, v121
	ds_read_b128 v[128:131], v187 offset:1552
	v_mul_f32_e32 v107, v234, v122
	v_mul_f32_e32 v109, v235, v123
	v_lshlrev_b32_e32 v144, 16, v6
	v_and_b32_e32 v145, 0xffff0000, v6
	v_lshlrev_b32_e32 v178, 16, v7
	v_and_b32_e32 v179, 0xffff0000, v7
	s_waitcnt lgkmcnt(3)
	v_pk_fma_f32 v[180:181], v[112:113], v[144:145], v[132:133]
	v_pk_fma_f32 v[230:231], v[114:115], v[178:179], v[134:135]
	v_lshlrev_b32_e32 v144, 16, v10
	v_and_b32_e32 v145, 0xffff0000, v10
	v_lshlrev_b32_e32 v178, 16, v11
	v_and_b32_e32 v179, 0xffff0000, v11
	s_waitcnt lgkmcnt(2)
	v_pk_fma_f32 v[180:181], v[236:237], v[144:145], v[180:181]
	v_pk_fma_f32 v[230:231], v[238:239], v[178:179], v[230:231]
	v_pk_fma_f32 v[232:233], v[112:113], v[144:145], v[132:133]
	v_pk_fma_f32 v[234:235], v[114:115], v[178:179], v[134:135]
	v_lshlrev_b32_e32 v144, 16, v14
	v_and_b32_e32 v145, 0xffff0000, v14
	v_lshlrev_b32_e32 v178, 16, v15
	v_and_b32_e32 v179, 0xffff0000, v15
	s_waitcnt lgkmcnt(1)
	v_pk_fma_f32 v[180:181], v[124:125], v[144:145], v[180:181]
	v_pk_fma_f32 v[230:231], v[126:127], v[178:179], v[230:231]
	v_pk_fma_f32 v[232:233], v[236:237], v[144:145], v[232:233]
	v_pk_fma_f32 v[234:235], v[238:239], v[178:179], v[234:235]
	v_lshlrev_b32_e32 v144, 16, v18
	v_and_b32_e32 v145, 0xffff0000, v18
	v_lshlrev_b32_e32 v178, 16, v19
	v_and_b32_e32 v179, 0xffff0000, v19
	s_waitcnt lgkmcnt(0)
; __device__ __forceinline__ unsigned pk2(float lo, float hi) { unsigned r; asm("v_cvt_pk_bf16_f32 %0, %1, %2" : "=v"(r) : "v"(lo), "v"(hi)); return r; }
; __device__ __forceinline__ float silu_f(float v) { return v * __builtin_amdgcn_rcpf(1.f + __expf(-v)); }
; __device__ __forceinline__ void conv_rows(const u32x4 (&rawp)[5], const float* wl, float (&o0)[8], float (&o1)[8]) {
;     float raw[5][8];
; #pragma unroll
;     for (int q = 0; q < 5; ++q) unpack8(rawp[q], raw[q]);
; #pragma unroll
;     for (int h = 0; h < 2; ++h) {
;         const f32x4 bv = *(const f32x4*)(wl + 4 * 128 + h * 4);
;         f32x4 a0 = bv, a1 = bv;
; #pragma unroll
;         for (int k = 0; k < 4; ++k) { const f32x4 wv = *(const f32x4*)(wl + k * 128 + h * 4);
; #pragma unroll
;             for (int i = 0; i < 4; ++i) { a0[i] += wv[i] * raw[k][h * 4 + i]; a1[i] += wv[i] * raw[k + 1][h * 4 + i]; } }
; #pragma unroll
;         for (int i = 0; i < 4; ++i) { o0[h * 4 + i] = silu_f(a0[i]); o1[h * 4 + i] = silu_f(a1[i]); }
;         __builtin_amdgcn_sched_barrier(0);
;     }
; }
; __device__ __forceinline__ void phase_ssd(const Params& p, uchar* sm, int j, bf16_t* zx, const float* dtraw, float* ssqb) {
;     ...
;             for (int i = 0; i < 8; ++i) *(unsigned*)(sm + L_XT + (c8 * 8 + i) * RS_T + ((lp ^ swz) * 4)) = pk2(xo0[i], xo1[i]);
;             {
;                 float t0[8], t1[8];
;                 __builtin_amdgcn_sched_barrier(0);
;                 conv_rows(rb, wlb, t0, t1);
	v_pk_fma_f32 v[180:181], v[128:129], v[144:145], v[180:181]
	v_pk_fma_f32 v[230:231], v[130:131], v[178:179], v[230:231]
	v_pk_fma_f32 v[232:233], v[124:125], v[144:145], v[232:233]
	v_pk_fma_f32 v[234:235], v[126:127], v[178:179], v[234:235]
	v_lshlrev_b32_e32 v144, 16, v26
	v_and_b32_e32 v145, 0xffff0000, v26
	v_lshlrev_b32_e32 v178, 16, v27
	v_and_b32_e32 v179, 0xffff0000, v27
	v_pk_fma_f32 v[232:233], v[128:129], v[144:145], v[232:233]
	v_pk_fma_f32 v[234:235], v[130:131], v[178:179], v[234:235]
	v_pk_mul_f32 v[96:97], v[180:181], v[100:101]
	v_pk_mul_f32 v[98:99], v[230:231], v[100:101]
	v_pk_mul_f32 v[120:121], v[232:233], v[100:101]
	v_pk_mul_f32 v[122:123], v[234:235], v[100:101]
	v_exp_f32_e32 v96, v96
	v_exp_f32_e32 v97, v97
	v_exp_f32_e32 v98, v98
	v_exp_f32_e32 v99, v99
	v_exp_f32_e32 v120, v120
	v_exp_f32_e32 v121, v121
	v_exp_f32_e32 v122, v122
	v_exp_f32_e32 v123, v123
	v_pk_add_f32 v[96:97], v[96:97], v[118:119]
	v_pk_add_f32 v[98:99], v[98:99], v[118:119]
	v_pk_add_f32 v[120:121], v[120:121], v[118:119]
	v_pk_add_f32 v[122:123], v[122:123], v[118:119]
	v_rcp_f32_e32 v96, v96
	v_rcp_f32_e32 v97, v97
	v_rcp_f32_e32 v98, v98
	v_rcp_f32_e32 v99, v99
	v_rcp_f32_e32 v120, v120
	v_rcp_f32_e32 v121, v121
	v_rcp_f32_e32 v122, v122
	v_rcp_f32_e32 v123, v123
	v_mul_f32_e32 v110, v180, v96
	v_mul_f32_e32 v112, v181, v97
	v_mul_f32_e32 v114, v230, v98
	v_mul_f32_e32 v116, v231, v99
	v_mul_f32_e32 v111, v232, v120
	v_mul_f32_e32 v113, v233, v121
	v_mul_f32_e32 v115, v234, v122
	v_mul_f32_e32 v117, v235, v123
	v_cvt_pk_bf16_f32 v96, v102, v103
	v_cvt_pk_bf16_f32 v97, v104, v105
	v_add_u32_e32 v98, 0xd000, v206
	ds_write2_b32 v98, v96, v97 offset1:36
	v_cvt_pk_bf16_f32 v96, v106, v107
	v_cvt_pk_bf16_f32 v97, v108, v109
	ds_write2_b32 v98, v96, v97 offset0:72 offset1:108
	v_cvt_pk_bf16_f32 v96, v110, v111
	v_cvt_pk_bf16_f32 v97, v112, v113
	ds_write2_b32 v98, v96, v97 offset0:144 offset1:180
	v_cvt_pk_bf16_f32 v96, v114, v115
	v_cvt_pk_bf16_f32 v97, v116, v117
	ds_write2_b32 v98, v96, v97 offset0:216 offset1:252
	ds_read_b128 v[232:235], v187 offset:4608
	ds_read_b128 v[96:99], v187 offset:2560
	ds_read_b128 v[124:127], v187 offset:3072
	ds_read_b128 v[128:131], v187 offset:3584
	v_mov_b32_e32 v144, 0xbfb8aa3b
	v_mov_b32_e32 v145, 0xbfb8aa3b
	ds_read_b128 v[132:135], v187 offset:4096
	v_mov_b32_e32 v178, 1.0
	v_mov_b32_e32 v179, 1.0
	s_waitcnt vmcnt(2)
	v_lshlrev_b32_e32 v180, 16, v20
	v_and_b32_e32 v181, 0xffff0000, v20
	v_lshlrev_b32_e32 v230, 16, v21
	v_and_b32_e32 v231, 0xffff0000, v21
	s_waitcnt lgkmcnt(3)
	v_pk_fma_f32 v[236:237], v[96:97], v[180:181], v[232:233]
	v_pk_fma_f32 v[238:239], v[98:99], v[230:231], v[234:235]
	v_lshlrev_b32_e32 v180, 16, v28
	v_and_b32_e32 v181, 0xffff0000, v28
	v_lshlrev_b32_e32 v230, 16, v29
	v_and_b32_e32 v231, 0xffff0000, v29
	s_waitcnt lgkmcnt(2)
	v_pk_fma_f32 v[236:237], v[124:125], v[180:181], v[236:237]
	v_pk_fma_f32 v[238:239], v[126:127], v[230:231], v[238:239]
	v_pk_fma_f32 v[246:247], v[96:97], v[180:181], v[232:233]
	v_pk_fma_f32 v[248:249], v[98:99], v[230:231], v[234:235]
	v_lshlrev_b32_e32 v180, 16, v32
	v_and_b32_e32 v181, 0xffff0000, v32
	v_lshlrev_b32_e32 v230, 16, v33
	v_and_b32_e32 v231, 0xffff0000, v33
	s_waitcnt lgkmcnt(1)
	v_pk_fma_f32 v[236:237], v[128:129], v[180:181], v[236:237]
	v_pk_fma_f32 v[238:239], v[130:131], v[230:231], v[238:239]
	v_pk_fma_f32 v[246:247], v[124:125], v[180:181], v[246:247]
	v_pk_fma_f32 v[248:249], v[126:127], v[230:231], v[248:249]
	v_lshlrev_b32_e32 v180, 16, v36
	v_and_b32_e32 v181, 0xffff0000, v36
	v_lshlrev_b32_e32 v230, 16, v37
	v_and_b32_e32 v231, 0xffff0000, v37
	s_waitcnt lgkmcnt(0)
	v_pk_fma_f32 v[236:237], v[132:133], v[180:181], v[236:237]
	v_pk_fma_f32 v[238:239], v[134:135], v[230:231], v[238:239]
	v_pk_fma_f32 v[246:247], v[128:129], v[180:181], v[246:247]
	v_pk_fma_f32 v[248:249], v[130:131], v[230:231], v[248:249]
	v_lshlrev_b32_e32 v180, 16, v40
	v_and_b32_e32 v181, 0xffff0000, v40
	v_lshlrev_b32_e32 v230, 16, v41
	v_and_b32_e32 v231, 0xffff0000, v41
	v_pk_fma_f32 v[246:247], v[132:133], v[180:181], v[246:247]
	v_pk_fma_f32 v[248:249], v[134:135], v[230:231], v[248:249]
	v_pk_mul_f32 v[96:97], v[236:237], v[144:145]
	v_pk_mul_f32 v[98:99], v[238:239], v[144:145]
	v_pk_mul_f32 v[124:125], v[246:247], v[144:145]
	v_pk_mul_f32 v[126:127], v[248:249], v[144:145]
	v_exp_f32_e32 v96, v96
	v_exp_f32_e32 v97, v97
	v_exp_f32_e32 v98, v98
	v_exp_f32_e32 v99, v99
	v_exp_f32_e32 v124, v124
	v_exp_f32_e32 v125, v125
	v_exp_f32_e32 v126, v126
	v_exp_f32_e32 v127, v127
	v_pk_add_f32 v[96:97], v[96:97], v[178:179]
	v_pk_add_f32 v[98:99], v[98:99], v[178:179]
	v_pk_add_f32 v[124:125], v[124:125], v[178:179]
	v_pk_add_f32 v[126:127], v[126:127], v[178:179]
	ds_read_b128 v[232:235], v187 offset:4624
	ds_read_b128 v[120:123], v187 offset:2576
	v_rcp_f32_e32 v96, v96
	v_rcp_f32_e32 v97, v97
	v_rcp_f32_e32 v98, v98
	v_rcp_f32_e32 v99, v99
	v_rcp_f32_e32 v124, v124
	v_rcp_f32_e32 v125, v125
	v_rcp_f32_e32 v126, v126
	v_rcp_f32_e32 v127, v127
	v_mul_f32_e32 v139, v236, v96
	v_mul_f32_e32 v229, v237, v97
	v_mul_f32_e32 v241, v238, v98
	v_mul_f32_e32 v243, v239, v99
	v_mul_f32_e32 v170, v246, v124
	v_mul_f32_e32 v240, v247, v125
	v_mul_f32_e32 v242, v248, v126
	v_mul_f32_e32 v244, v249, v127
	ds_read_b128 v[124:127], v187 offset:3088
	ds_read_b128 v[128:131], v187 offset:3600
	ds_read_b128 v[132:135], v187 offset:4112
	v_lshlrev_b32_e32 v180, 16, v22
	v_and_b32_e32 v181, 0xffff0000, v22
	v_lshlrev_b32_e32 v230, 16, v23
	v_and_b32_e32 v231, 0xffff0000, v23
	s_waitcnt lgkmcnt(3)
; __device__ __forceinline__ unsigned pk2(float lo, float hi) { unsigned r; asm("v_cvt_pk_bf16_f32 %0, %1, %2" : "=v"(r) : "v"(lo), "v"(hi)); return r; }
; __device__ __forceinline__ u32x4 pack8(const float (&o)[8]) { u32x4 r; r.x = pk2(o[0], o[1]); r.y = pk2(o[2], o[3]); r.z = pk2(o[4], o[5]); r.w = pk2(o[6], o[7]); return r; }
; __device__ __forceinline__ float silu_f(float v) { return v * __builtin_amdgcn_rcpf(1.f + __expf(-v)); }
; __device__ __forceinline__ void conv_rows(const u32x4 (&rawp)[5], const float* wl, float (&o0)[8], float (&o1)[8]) {
;     float raw[5][8];
; #pragma unroll
;     for (int q = 0; q < 5; ++q) unpack8(rawp[q], raw[q]);
; #pragma unroll
;     for (int h = 0; h < 2; ++h) {
;         const f32x4 bv = *(const f32x4*)(wl + 4 * 128 + h * 4);
;         f32x4 a0 = bv, a1 = bv;
; #pragma unroll
;         for (int k = 0; k < 4; ++k) { const f32x4 wv = *(const f32x4*)(wl + k * 128 + h * 4);
; #pragma unroll
;             for (int i = 0; i < 4; ++i) { a0[i] += wv[i] * raw[k][h * 4 + i]; a1[i] += wv[i] * raw[k + 1][h * 4 + i]; } }
; #pragma unroll
;         for (int i = 0; i < 4; ++i) { o0[h * 4 + i] = silu_f(a0[i]); o1[h * 4 + i] = silu_f(a1[i]); }
;         __builtin_amdgcn_sched_barrier(0);
;     }
; }
; __device__ __forceinline__ void phase_ssd(const Params& p, uchar* sm, int j, bf16_t* zx, const float* dtraw, float* ssqb) {
;     ...
;                 conv_rows(rb, wlb, t0, t1);
;                 __builtin_amdgcn_sched_barrier(0);
;                 *(u32x4*)(sm + L_B + (2 * lp) * RS_CB + c8 * 16) = pack8(t0);
;                 *(u32x4*)(sm + L_B + (2 * lp + 1) * RS_CB + c8 * 16) = pack8(t1);
; #pragma unroll
;                 for (int i = 0; i < 8; ++i) *(unsigned*)(sm + L_BT + (c8 * 8 + i) * RS_T + ((lp ^ swz) * 4)) = pk2(t0[i], t1[i]);
;                 __builtin_amdgcn_sched_barrier(0);
;                 conv_rows(rc, wlc, t0, t1);
	v_pk_fma_f32 v[236:237], v[120:121], v[180:181], v[232:233]
	v_pk_fma_f32 v[238:239], v[122:123], v[230:231], v[234:235]
	v_lshlrev_b32_e32 v180, 16, v30
	v_and_b32_e32 v181, 0xffff0000, v30
	v_lshlrev_b32_e32 v230, 16, v31
	v_and_b32_e32 v231, 0xffff0000, v31
	s_waitcnt lgkmcnt(2)
	v_pk_fma_f32 v[236:237], v[124:125], v[180:181], v[236:237]
	v_pk_fma_f32 v[238:239], v[126:127], v[230:231], v[238:239]
	v_pk_fma_f32 v[246:247], v[120:121], v[180:181], v[232:233]
	v_pk_fma_f32 v[248:249], v[122:123], v[230:231], v[234:235]
	v_lshlrev_b32_e32 v180, 16, v34
	v_and_b32_e32 v181, 0xffff0000, v34
	v_lshlrev_b32_e32 v230, 16, v35
	v_and_b32_e32 v231, 0xffff0000, v35
	s_waitcnt lgkmcnt(1)
	v_pk_fma_f32 v[236:237], v[128:129], v[180:181], v[236:237]
	v_pk_fma_f32 v[238:239], v[130:131], v[230:231], v[238:239]
	v_pk_fma_f32 v[246:247], v[124:125], v[180:181], v[246:247]
	v_pk_fma_f32 v[248:249], v[126:127], v[230:231], v[248:249]
	v_lshlrev_b32_e32 v180, 16, v38
	v_and_b32_e32 v181, 0xffff0000, v38
	v_lshlrev_b32_e32 v230, 16, v39
	v_and_b32_e32 v231, 0xffff0000, v39
	s_waitcnt lgkmcnt(0)
	v_pk_fma_f32 v[236:237], v[132:133], v[180:181], v[236:237]
	v_pk_fma_f32 v[238:239], v[134:135], v[230:231], v[238:239]
	v_pk_fma_f32 v[246:247], v[128:129], v[180:181], v[246:247]
	v_pk_fma_f32 v[248:249], v[130:131], v[230:231], v[248:249]
	v_lshlrev_b32_e32 v180, 16, v42
	v_and_b32_e32 v181, 0xffff0000, v42
	v_lshlrev_b32_e32 v230, 16, v43
	v_and_b32_e32 v231, 0xffff0000, v43
	v_pk_fma_f32 v[246:247], v[132:133], v[180:181], v[246:247]
	v_pk_fma_f32 v[248:249], v[134:135], v[230:231], v[248:249]
	v_pk_mul_f32 v[96:97], v[236:237], v[144:145]
	v_pk_mul_f32 v[98:99], v[238:239], v[144:145]
	v_pk_mul_f32 v[124:125], v[246:247], v[144:145]
	v_pk_mul_f32 v[126:127], v[248:249], v[144:145]
	v_exp_f32_e32 v96, v96
	v_exp_f32_e32 v97, v97
	v_exp_f32_e32 v98, v98
	v_exp_f32_e32 v99, v99
	v_exp_f32_e32 v124, v124
	v_exp_f32_e32 v125, v125
	v_exp_f32_e32 v126, v126
	v_exp_f32_e32 v127, v127
	v_pk_add_f32 v[96:97], v[96:97], v[178:179]
	v_pk_add_f32 v[98:99], v[98:99], v[178:179]
	v_pk_add_f32 v[124:125], v[124:125], v[178:179]
	v_pk_add_f32 v[126:127], v[126:127], v[178:179]
	v_rcp_f32_e32 v96, v96
	v_rcp_f32_e32 v97, v97
	v_rcp_f32_e32 v98, v98
	v_rcp_f32_e32 v99, v99
	v_rcp_f32_e32 v124, v124
	v_rcp_f32_e32 v125, v125
	v_rcp_f32_e32 v126, v126
	v_rcp_f32_e32 v127, v127
	v_mul_f32_e32 v119, v236, v96
	v_mul_f32_e32 v100, v237, v97
	v_mul_f32_e32 v120, v238, v98
	v_mul_f32_e32 v101, v239, v99
	v_mul_f32_e32 v121, v246, v124
	v_mul_f32_e32 v122, v247, v125
	v_mul_f32_e32 v118, v248, v126
	v_mul_f32_e32 v123, v249, v127
	v_cvt_pk_bf16_f32 v96, v139, v229
	v_cvt_pk_bf16_f32 v97, v241, v243
	v_cvt_pk_bf16_f32 v98, v119, v100
	v_cvt_pk_bf16_f32 v99, v120, v101
	ds_write_b128 v207, v[96:99] offset:17408
	v_cvt_pk_bf16_f32 v96, v170, v240
	v_cvt_pk_bf16_f32 v97, v242, v244
	v_cvt_pk_bf16_f32 v98, v121, v122
	v_cvt_pk_bf16_f32 v99, v118, v123
	ds_write_b128 v208, v[96:99] offset:17408
	v_cvt_pk_bf16_f32 v96, v139, v170
	v_cvt_pk_bf16_f32 v97, v229, v240
	v_add_u32_e32 v98, 0x8800, v206
	ds_write2_b32 v98, v96, v97 offset1:36
	v_cvt_pk_bf16_f32 v96, v241, v242
	v_cvt_pk_bf16_f32 v97, v243, v244
	ds_write2_b32 v98, v96, v97 offset0:72 offset1:108
	v_cvt_pk_bf16_f32 v96, v119, v121
	v_cvt_pk_bf16_f32 v97, v100, v122
	ds_write2_b32 v98, v96, v97 offset0:144 offset1:180
	v_cvt_pk_bf16_f32 v96, v120, v118
	v_cvt_pk_bf16_f32 v97, v101, v123
	ds_write2_b32 v98, v96, v97 offset0:216 offset1:252
	ds_read_b128 v[236:239], v187 offset:7168
	ds_read_b128 v[124:127], v187 offset:5120
	ds_read_b128 v[128:131], v187 offset:5632
	ds_read_b128 v[132:135], v187 offset:6144
	v_mov_b32_e32 v96, 0xbfb8aa3b
	v_mov_b32_e32 v97, 0xbfb8aa3b
	ds_read_b128 v[232:235], v187 offset:6656
	v_mov_b32_e32 v144, 1.0
	v_mov_b32_e32 v145, 1.0
	v_lshlrev_b32_e32 v178, 16, v44
	v_and_b32_e32 v179, 0xffff0000, v44
	v_lshlrev_b32_e32 v180, 16, v45
	v_and_b32_e32 v181, 0xffff0000, v45
	s_waitcnt lgkmcnt(3)
	v_pk_fma_f32 v[230:231], v[124:125], v[178:179], v[236:237]
	v_pk_fma_f32 v[246:247], v[126:127], v[180:181], v[238:239]
	v_lshlrev_b32_e32 v178, 16, v48
	v_and_b32_e32 v179, 0xffff0000, v48
	v_lshlrev_b32_e32 v180, 16, v49
	v_and_b32_e32 v181, 0xffff0000, v49
	s_waitcnt lgkmcnt(2)
	v_pk_fma_f32 v[230:231], v[128:129], v[178:179], v[230:231]
	v_pk_fma_f32 v[246:247], v[130:131], v[180:181], v[246:247]
	v_pk_fma_f32 v[248:249], v[124:125], v[178:179], v[236:237]
	v_pk_fma_f32 v[250:251], v[126:127], v[180:181], v[238:239]
	v_lshlrev_b32_e32 v178, 16, v52
	v_and_b32_e32 v179, 0xffff0000, v52
	v_lshlrev_b32_e32 v180, 16, v53
	v_and_b32_e32 v181, 0xffff0000, v53
	s_waitcnt lgkmcnt(1)
	v_pk_fma_f32 v[230:231], v[132:133], v[178:179], v[230:231]
	v_pk_fma_f32 v[246:247], v[134:135], v[180:181], v[246:247]
	v_pk_fma_f32 v[248:249], v[128:129], v[178:179], v[248:249]
	v_pk_fma_f32 v[250:251], v[130:131], v[180:181], v[250:251]
	v_lshlrev_b32_e32 v178, 16, v56
	v_and_b32_e32 v179, 0xffff0000, v56
	v_lshlrev_b32_e32 v180, 16, v57
	v_and_b32_e32 v181, 0xffff0000, v57
	s_waitcnt lgkmcnt(0)
; __device__ __forceinline__ u32x4 pack8(const float (&o)[8]) { u32x4 r; r.x = pk2(o[0], o[1]); r.y = pk2(o[2], o[3]); r.z = pk2(o[4], o[5]); r.w = pk2(o[6], o[7]); return r; }
; __device__ __forceinline__ float silu_f(float v) { return v * __builtin_amdgcn_rcpf(1.f + __expf(-v)); }
; __device__ __forceinline__ void conv_rows(const u32x4 (&rawp)[5], const float* wl, float (&o0)[8], float (&o1)[8]) {
;     float raw[5][8];
; #pragma unroll
;     for (int q = 0; q < 5; ++q) unpack8(rawp[q], raw[q]);
; #pragma unroll
;     for (int h = 0; h < 2; ++h) {
;         const f32x4 bv = *(const f32x4*)(wl + 4 * 128 + h * 4);
;         f32x4 a0 = bv, a1 = bv;
; #pragma unroll
;         for (int k = 0; k < 4; ++k) { const f32x4 wv = *(const f32x4*)(wl + k * 128 + h * 4);
; #pragma unroll
;             for (int i = 0; i < 4; ++i) { a0[i] += wv[i] * raw[k][h * 4 + i]; a1[i] += wv[i] * raw[k + 1][h * 4 + i]; } }
; #pragma unroll
;         for (int i = 0; i < 4; ++i) { o0[h * 4 + i] = silu_f(a0[i]); o1[h * 4 + i] = silu_f(a1[i]); }
;         __builtin_amdgcn_sched_barrier(0);
;     }
; }
; __device__ __forceinline__ void phase_ssd(const Params& p, uchar* sm, int j, bf16_t* zx, const float* dtraw, float* ssqb) {
;     ...
;                 conv_rows(rc, wlc, t0, t1);
;                 __builtin_amdgcn_sched_barrier(0);
;                 *(u32x4*)(sm + L_C + (2 * lp) * RS_CB + c8 * 16) = pack8(t0);
;                 *(u32x4*)(sm + L_C + (2 * lp + 1) * RS_CB + c8 * 16) = pack8(t1);
;             }
;             const u32x4 xp0 = pack8(xo0), xp1 = pack8(xo1);
;             bf16_t* zc = zx + (size_t)zrow0 * LDZ;
;             if (c + 1 < 32) { const bf16_t* zb = zc + 64 * LDZ;
;                 load_raw(zb + 2048 + colx, toff, false, 2 * lp, rx); }
	v_pk_fma_f32 v[230:231], v[232:233], v[178:179], v[230:231]
	v_pk_fma_f32 v[246:247], v[234:235], v[180:181], v[246:247]
	v_pk_fma_f32 v[248:249], v[132:133], v[178:179], v[248:249]
	v_pk_fma_f32 v[250:251], v[134:135], v[180:181], v[250:251]
	v_lshlrev_b32_e32 v178, 16, v60
	v_and_b32_e32 v179, 0xffff0000, v60
	v_lshlrev_b32_e32 v180, 16, v61
	v_and_b32_e32 v181, 0xffff0000, v61
	v_pk_fma_f32 v[248:249], v[232:233], v[178:179], v[248:249]
	v_pk_fma_f32 v[250:251], v[234:235], v[180:181], v[250:251]
	v_pk_mul_f32 v[124:125], v[230:231], v[96:97]
	v_pk_mul_f32 v[126:127], v[246:247], v[96:97]
	v_pk_mul_f32 v[128:129], v[248:249], v[96:97]
	v_pk_mul_f32 v[130:131], v[250:251], v[96:97]
	v_exp_f32_e32 v124, v124
	v_exp_f32_e32 v125, v125
	v_exp_f32_e32 v126, v126
	v_exp_f32_e32 v127, v127
	v_exp_f32_e32 v128, v128
	v_exp_f32_e32 v129, v129
	v_exp_f32_e32 v130, v130
	v_exp_f32_e32 v131, v131
	v_pk_add_f32 v[124:125], v[124:125], v[144:145]
	v_pk_add_f32 v[126:127], v[126:127], v[144:145]
	v_pk_add_f32 v[128:129], v[128:129], v[144:145]
	v_pk_add_f32 v[130:131], v[130:131], v[144:145]
	ds_read_b128 v[236:239], v187 offset:7184
	ds_read_b128 v[120:123], v187 offset:5136
	v_rcp_f32_e32 v124, v124
	v_rcp_f32_e32 v125, v125
	v_rcp_f32_e32 v126, v126
	v_rcp_f32_e32 v127, v127
	v_rcp_f32_e32 v128, v128
	v_rcp_f32_e32 v129, v129
	v_rcp_f32_e32 v130, v130
	v_rcp_f32_e32 v131, v131
	v_mul_f32_e32 v139, v230, v124
	v_mul_f32_e32 v229, v231, v125
	v_mul_f32_e32 v241, v246, v126
	v_mul_f32_e32 v243, v247, v127
	v_mul_f32_e32 v170, v248, v128
	v_mul_f32_e32 v240, v249, v129
	v_mul_f32_e32 v242, v250, v130
	v_mul_f32_e32 v244, v251, v131
	ds_read_b128 v[128:131], v187 offset:5648
	ds_read_b128 v[132:135], v187 offset:6160
	ds_read_b128 v[232:235], v187 offset:6672
	v_lshlrev_b32_e32 v178, 16, v46
	v_and_b32_e32 v179, 0xffff0000, v46
	v_lshlrev_b32_e32 v180, 16, v47
	v_and_b32_e32 v181, 0xffff0000, v47
	s_waitcnt lgkmcnt(3)
	v_pk_fma_f32 v[230:231], v[120:121], v[178:179], v[236:237]
	v_pk_fma_f32 v[246:247], v[122:123], v[180:181], v[238:239]
	v_lshlrev_b32_e32 v178, 16, v50
	v_and_b32_e32 v179, 0xffff0000, v50
	v_lshlrev_b32_e32 v180, 16, v51
	v_and_b32_e32 v181, 0xffff0000, v51
	s_waitcnt lgkmcnt(2)
	v_pk_fma_f32 v[230:231], v[128:129], v[178:179], v[230:231]
	v_pk_fma_f32 v[246:247], v[130:131], v[180:181], v[246:247]
	v_pk_fma_f32 v[248:249], v[120:121], v[178:179], v[236:237]
	v_pk_fma_f32 v[250:251], v[122:123], v[180:181], v[238:239]
	v_lshlrev_b32_e32 v178, 16, v54
	v_and_b32_e32 v179, 0xffff0000, v54
	v_lshlrev_b32_e32 v180, 16, v55
	v_and_b32_e32 v181, 0xffff0000, v55
	s_waitcnt lgkmcnt(1)
	v_pk_fma_f32 v[230:231], v[132:133], v[178:179], v[230:231]
	v_pk_fma_f32 v[246:247], v[134:135], v[180:181], v[246:247]
	v_pk_fma_f32 v[248:249], v[128:129], v[178:179], v[248:249]
	v_pk_fma_f32 v[250:251], v[130:131], v[180:181], v[250:251]
	v_lshlrev_b32_e32 v178, 16, v58
	v_and_b32_e32 v179, 0xffff0000, v58
	v_lshlrev_b32_e32 v180, 16, v59
	v_and_b32_e32 v181, 0xffff0000, v59
	s_waitcnt lgkmcnt(0)
	v_pk_fma_f32 v[230:231], v[232:233], v[178:179], v[230:231]
	v_pk_fma_f32 v[246:247], v[234:235], v[180:181], v[246:247]
	v_pk_fma_f32 v[248:249], v[132:133], v[178:179], v[248:249]
	v_pk_fma_f32 v[250:251], v[134:135], v[180:181], v[250:251]
	v_lshlrev_b32_e32 v178, 16, v62
	v_and_b32_e32 v179, 0xffff0000, v62
	v_lshlrev_b32_e32 v180, 16, v63
	v_and_b32_e32 v181, 0xffff0000, v63
	v_pk_fma_f32 v[248:249], v[232:233], v[178:179], v[248:249]
	v_pk_fma_f32 v[250:251], v[234:235], v[180:181], v[250:251]
	v_pk_mul_f32 v[124:125], v[230:231], v[96:97]
	v_pk_mul_f32 v[126:127], v[246:247], v[96:97]
	v_pk_mul_f32 v[128:129], v[248:249], v[96:97]
	v_pk_mul_f32 v[130:131], v[250:251], v[96:97]
	v_exp_f32_e32 v124, v124
	v_exp_f32_e32 v125, v125
	v_exp_f32_e32 v126, v126
	v_exp_f32_e32 v127, v127
	v_exp_f32_e32 v128, v128
	v_exp_f32_e32 v129, v129
	v_exp_f32_e32 v130, v130
	v_exp_f32_e32 v131, v131
	v_pk_add_f32 v[124:125], v[124:125], v[144:145]
	v_pk_add_f32 v[126:127], v[126:127], v[144:145]
	v_pk_add_f32 v[128:129], v[128:129], v[144:145]
	v_pk_add_f32 v[130:131], v[130:131], v[144:145]
	v_rcp_f32_e32 v124, v124
	v_rcp_f32_e32 v125, v125
	v_rcp_f32_e32 v126, v126
	v_rcp_f32_e32 v127, v127
	v_rcp_f32_e32 v128, v128
	v_rcp_f32_e32 v129, v129
	v_rcp_f32_e32 v130, v130
	v_rcp_f32_e32 v131, v131
	v_mul_f32_e32 v119, v230, v124
	v_mul_f32_e32 v99, v231, v125
	v_mul_f32_e32 v120, v246, v126
	v_mul_f32_e32 v101, v247, v127
	v_mul_f32_e32 v121, v248, v128
	v_mul_f32_e32 v122, v249, v129
	v_mul_f32_e32 v100, v250, v130
	v_mul_f32_e32 v118, v251, v131
	v_readlane_b32 s60, v254, 0
	s_cmp_lg_u32 s83, 1
	v_readlane_b32 s66, v254, 6
	v_readlane_b32 s67, v254, 7
	v_cvt_pk_bf16_f32 v96, v139, v229
	v_cvt_pk_bf16_f32 v97, v241, v243
	v_cvt_pk_bf16_f32 v98, v119, v99
	v_cvt_pk_bf16_f32 v99, v120, v101
	v_cvt_pk_bf16_f32 v235, v102, v104
	v_cvt_pk_bf16_f32 v231, v103, v105
	s_cselect_b64 s[0:1], -1, 0
	s_cmp_eq_u32 s83, 1
	v_lshl_add_u64 v[104:105], s[66:67], 0, v[174:175]
	ds_write_b128 v207, v[96:99]
	v_cvt_pk_bf16_f32 v96, v170, v240
	v_cvt_pk_bf16_f32 v97, v242, v244
	v_cvt_pk_bf16_f32 v98, v121, v122
	v_cvt_pk_bf16_f32 v99, v100, v118
	ds_write_b128 v208, v[96:99]
	v_cvt_pk_bf16_f32 v233, v106, v108
	v_cvt_pk_bf16_f32 v236, v110, v112
	v_cvt_pk_bf16_f32 v234, v114, v116
	v_cvt_pk_bf16_f32 v229, v107, v109
	v_cvt_pk_bf16_f32 v232, v111, v113
	v_cvt_pk_bf16_f32 v230, v115, v117
	v_readlane_b32 s61, v254, 1
	v_readlane_b32 s62, v254, 2
	v_readlane_b32 s63, v254, 3
	v_readlane_b32 s64, v254, 4
	v_readlane_b32 s65, v254, 5
	s_cbranch_scc1 .LBB0_468
	v_add_co_u32_e32 v4, vcc, 0x64d5000, v104
	s_nop 1
	v_addc_co_u32_e32 v5, vcc, 0, v105, vcc
	v_add_co_u32_e32 v8, vcc, 0x64d8000, v104
	s_nop 1
	v_addc_co_u32_e32 v9, vcc, 0, v105, vcc
	v_add_co_u32_e32 v12, vcc, 0x64db000, v104
	global_load_dwordx4 v[4:7], v[4:5], off offset:3712
	s_nop 0
	global_load_dwordx4 v[8:11], v[8:9], off offset:3840
	v_addc_co_u32_e32 v13, vcc, 0, v105, vcc
	v_add_co_u32_e32 v16, vcc, 0x64df000, v104
	s_nop 1
	v_addc_co_u32_e32 v17, vcc, 0, v105, vcc
	v_add_co_u32_e32 v24, vcc, 0x64e2000, v104
	global_load_dwordx4 v[12:15], v[12:13], off offset:3968
	s_nop 0
	global_load_dwordx4 v[16:19], v[16:17], off
	v_addc_co_u32_e32 v25, vcc, 0, v105, vcc
	global_load_dwordx4 v[24:27], v[24:25], off offset:128
